# load-width lever completed: the last 8-byte gate-load pair merged into a 16-byte load via register renaming
# baseline (speedup 1.0000x reference)
.LBB0_927:
	s_or_b64 exec, exec, s[26:27]
	v_or_b32_e32 v114, 16, v138
	v_ashrrev_i32_e32 v115, 31, v114
	v_lshlrev_b64 v[116:117], 10, v[114:115]
	v_lshl_add_u64 v[124:125], v[116:117], 0, v[136:137]
	v_lshlrev_b64 v[126:127], 2, v[124:125]
	v_lshlrev_b64 v[124:125], 1, v[124:125]
	v_lshl_add_u64 v[128:129], s[28:29], 0, v[126:127]
	v_lshl_add_u64 v[144:145], s[46:47], 0, v[124:125]
	global_load_dwordx4 v[116:119], v[128:129], off offset:16
	global_load_dwordx4 v[120:123], v[128:129], off
	global_load_dwordx4 v[146:149], v[144:145], off sc1
	v_lshl_add_u64 v[126:127], s[34:35], 0, v[126:127]
	v_lshl_add_u64 v[124:125], s[36:37], 0, v[124:125]
	s_waitcnt vmcnt(0)
	v_lshlrev_b32_e32 v139, 16, v146
	v_and_b32_e32 v146, 0xffff0000, v146
	v_lshlrev_b32_e32 v150, 16, v147
	v_and_b32_e32 v147, 0xffff0000, v147
	s_waitcnt vmcnt(0)
	v_lshlrev_b32_e32 v151, 16, v148
	v_and_b32_e32 v148, 0xffff0000, v148
	v_lshlrev_b32_e32 v152, 16, v149
	v_and_b32_e32 v149, 0xffff0000, v149
	v_mul_f32_e32 v110, v110, v139
	v_mul_f32_e32 v111, v111, v146
	v_mul_f32_e32 v112, v112, v150
	v_mul_f32_e32 v113, v113, v147
	v_mul_f32_e32 v146, v106, v151
	v_mul_f32_e32 v147, v107, v148
	v_mul_f32_e32 v148, v108, v152
	v_mul_f32_e32 v149, v109, v149
	v_pk_add_f32 v[108:109], v[122:123], v[112:113]
	v_pk_add_f32 v[106:107], v[120:121], v[110:111]
	v_pk_add_f32 v[112:113], v[118:119], v[148:149]
	v_pk_add_f32 v[110:111], v[116:117], v[146:147]
	v_cvt_pk_bf16_f32 v116, v106, v107
	v_cvt_pk_bf16_f32 v117, v108, v109
	v_cvt_pk_bf16_f32 v118, v110, v111
	v_cvt_pk_bf16_f32 v119, v112, v113
	global_store_dwordx4 v[126:127], v[106:109], off
	global_store_dwordx4 v[126:127], v[110:113], off offset:16
	global_store_dwordx4 v[124:125], v[116:119], off
	global_load_dwordx4 v[116:119], v[128:129], off offset:528
	s_nop 0
	global_load_dwordx4 v[120:123], v[128:129], off offset:512
	s_nop 0
	global_load_dwordx4 v[144:147], v[144:145], off offset:256 sc1
	v_mul_f32_e32 v107, v107, v107
	v_mul_f32_e32 v109, v109, v109
	v_mul_f32_e32 v111, v111, v111
	v_mul_f32_e32 v113, v113, v113
	v_fmac_f32_e32 v107, v106, v106
	v_fmac_f32_e32 v109, v108, v108
	v_fmac_f32_e32 v111, v110, v110
	v_fmac_f32_e32 v113, v112, v112
	v_add_f32_e32 v106, v107, v109
	v_add_f32_e32 v107, v111, v113
	v_add_f32_e32 v110, v106, v107
	s_waitcnt vmcnt(0)
	v_lshlrev_b32_e32 v106, 16, v144
	v_and_b32_e32 v107, 0xffff0000, v144
	v_lshlrev_b32_e32 v108, 16, v145
	v_and_b32_e32 v109, 0xffff0000, v145
	s_waitcnt vmcnt(0)
	v_lshlrev_b32_e32 v111, 16, v146
	v_and_b32_e32 v112, 0xffff0000, v146
	v_lshlrev_b32_e32 v113, 16, v147
	v_and_b32_e32 v128, 0xffff0000, v147
	v_mul_f32_e32 v102, v102, v106
	v_mul_f32_e32 v103, v103, v107
	v_mul_f32_e32 v104, v104, v108
	v_mul_f32_e32 v105, v105, v109
	v_mul_f32_e32 v106, v98, v111
	v_mul_f32_e32 v107, v99, v112
	v_mul_f32_e32 v108, v100, v113
	v_mul_f32_e32 v109, v101, v128
	v_pk_add_f32 v[100:101], v[122:123], v[104:105]
	v_pk_add_f32 v[98:99], v[120:121], v[102:103]
	v_pk_add_f32 v[104:105], v[118:119], v[108:109]
	v_pk_add_f32 v[102:103], v[116:117], v[106:107]
	global_store_dwordx4 v[126:127], v[98:101], off offset:512
	global_store_dwordx4 v[126:127], v[102:105], off offset:528
	v_cvt_pk_bf16_f32 v106, v98, v99
	v_cvt_pk_bf16_f32 v107, v100, v101
	v_cvt_pk_bf16_f32 v108, v102, v103
	v_cvt_pk_bf16_f32 v109, v104, v105
	v_mul_f32_e32 v99, v99, v99
	v_mul_f32_e32 v101, v101, v101
	v_mul_f32_e32 v103, v103, v103
	v_mul_f32_e32 v105, v105, v105
	v_fmac_f32_e32 v99, v98, v98
	v_fmac_f32_e32 v101, v100, v100
	v_fmac_f32_e32 v103, v102, v102
	v_fmac_f32_e32 v105, v104, v104
	global_store_dwordx4 v[124:125], v[106:109], off offset:256
	v_mbcnt_lo_u32_b32 v98, -1, 0
	v_mbcnt_hi_u32_b32 v98, -1, v98
	v_add_f32_e32 v99, v99, v101
	v_add_f32_e32 v100, v103, v105
	v_lshlrev_b32_e32 v98, 2, v98
	v_add_f32_e32 v99, v99, v100
	v_xor_b32_e32 v98, 64, v98
	v_add_f32_e32 v99, v110, v99
	ds_bpermute_b32 v98, v98, v99
	s_waitcnt lgkmcnt(0)
	v_add_f32_e32 v98, v99, v98
	v_mov_b32_e32 v99, v98
	s_nop 1
	v_permlane32_swap_b32_e32 v98, v99
	s_mov_b64 s[26:27], exec
	v_readlane_b32 s80, v254, 53
	s_and_b64 s[30:31], s[26:27], s[42:43]
	v_readlane_b32 s81, v254, 54
	v_readlane_b32 s84, v254, 57
	v_readlane_b32 s64, v254, 60
	v_readlane_b32 s65, v254, 61
	v_readlane_b32 s77, v254, 62
	v_readlane_b32 s78, v254, 63
	v_readlane_b32 s76, v255, 1
	v_readlane_b32 s66, v255, 4
	v_readlane_b32 s67, v255, 6
	v_mov_b64_e32 v[212:213], 0x100
	v_mov_b64_e32 v[216:217], 0xff
	s_mov_b64 exec, s[30:31]
	s_cbranch_execz .LBB0_929
	v_lshlrev_b64 v[100:101], 6, v[114:115]
	v_lshl_add_u64 v[100:101], s[38:39], 0, v[100:101]
	v_lshl_add_u64 v[100:101], s[60:61], 2, v[100:101]
	s_lshl_b32 s90, s73, 2
	v_lshl_add_u64 v[100:101], v[100:101], 0, s[90:91]
	v_add_f32_e32 v98, v98, v99
	global_store_dword v[100:101], v98, off
